# NSA compressed branch: K-fragment reads batched ahead of the chained MFMAs (pass 1 loop, pass 2 kt=1) and P.V fragment reads batched per 4-MFMA group
# baseline (speedup 1.0000x reference)
.LBB0_309:
	v_add_u32_e32 v23, s25, v20
	ds_read_b128 v[2:5], v23
	ds_read_b128 v[24:27], v23 offset:32
	ds_read_b128 v[32:35], v23 offset:64
	ds_read_b128 v[36:39], v23 offset:96
	ds_read_b128 v[40:43], v23 offset:128
	ds_read_b128 v[44:47], v23 offset:160
	ds_read_b128 v[48:51], v23 offset:192
	ds_read_b128 v[52:55], v23 offset:224
	v_cvt_f32_i32_e32 v28, v19
	v_cmp_lt_i32_e32 vcc, 30, v19
	v_cmp_lt_i32_e64 s[40:41], 46, v19
	v_cmp_lt_i32_e64 s[42:43], 62, v19
	v_cmp_lt_i32_e64 s[44:45], s0, v19
	v_cmp_lt_i32_e64 s[68:69], s80, v19
	v_cmp_lt_i32_e64 s[46:47], s28, v19
	s_waitcnt lgkmcnt(7)
	v_mfma_f32_32x32x16_bf16 v[2:17], v[2:5], v[82:85], 0
	v_cmp_lt_i32_e64 s[48:49], s29, v19
	v_cmp_lt_i32_e64 s[50:51], s30, v19
	v_cmp_lt_i32_e64 s[52:53], s31, v19
	v_cmp_lt_i32_e64 s[54:55], s34, v19
	v_cmp_lt_i32_e64 s[56:57], s94, v19
	v_cmp_lt_i32_e64 s[58:59], s95, v19
	v_cmp_lt_i32_e64 s[60:61], s73, v19
	s_waitcnt lgkmcnt(6)
	v_mfma_f32_32x32x16_bf16 v[2:17], v[24:27], v[86:89], v[2:17]
	v_cmp_lt_i32_e64 s[62:63], s3, v19
	v_cmp_lt_i32_e64 s[64:65], s89, v19
	v_cmp_lt_i32_e64 s[66:67], s1, v19
	v_mov_b32_e32 v21, v22
	v_mov_b32_e32 v22, v139
	s_addk_i32 s25, 0x2200
	v_add_u32_e32 v19, 0xfffffe00, v19
	s_waitcnt lgkmcnt(5)
	v_mfma_f32_32x32x16_bf16 v[2:17], v[32:35], v[90:93], v[2:17]
	s_cmpk_lg_u32 s25, 0x8800
	s_waitcnt lgkmcnt(4)
	v_mfma_f32_32x32x16_bf16 v[2:17], v[36:39], v[94:97], v[2:17]
	s_waitcnt lgkmcnt(3)
	v_mfma_f32_32x32x16_bf16 v[2:17], v[40:43], v[98:101], v[2:17]
	s_waitcnt lgkmcnt(2)
	v_mfma_f32_32x32x16_bf16 v[2:17], v[44:47], v[102:105], v[2:17]
	s_waitcnt lgkmcnt(1)
	v_mfma_f32_32x32x16_bf16 v[2:17], v[48:51], v[106:109], v[2:17]
	v_add_f32_e32 v23, 0xc1780000, v28
	v_mul_f32_e64 v23, v23, -v119
	s_waitcnt lgkmcnt(0)
	v_mfma_f32_32x32x16_bf16 v[2:17], v[52:55], v[110:113], v[2:17]
	s_nop 11
	v_fmamk_f32 v2, v2, 0x3e0293ee, v23
	v_fmamk_f32 v3, v3, 0x3e0293ee, v23
	v_fmamk_f32 v4, v4, 0x3e0293ee, v23
	v_fmamk_f32 v5, v5, 0x3e0293ee, v23
	v_fmamk_f32 v6, v6, 0x3e0293ee, v23
	v_fmamk_f32 v7, v7, 0x3e0293ee, v23
	v_fmamk_f32 v8, v8, 0x3e0293ee, v23
	v_fmamk_f32 v9, v9, 0x3e0293ee, v23
	v_fmamk_f32 v10, v10, 0x3e0293ee, v23
	v_fmamk_f32 v11, v11, 0x3e0293ee, v23
	v_fmamk_f32 v12, v12, 0x3e0293ee, v23
	v_fmamk_f32 v13, v13, 0x3e0293ee, v23
	v_fmamk_f32 v14, v14, 0x3e0293ee, v23
	v_fmamk_f32 v15, v15, 0x3e0293ee, v23
	v_fmamk_f32 v16, v16, 0x3e0293ee, v23
	v_fmac_f32_e32 v23, 0x3e0293ee, v17
	v_fmac_f32_e32 v2, 0, v119
	v_fmac_f32_e32 v3, 0x41800000, v119
	v_fmac_f32_e32 v4, 0x42000000, v119
	v_fmac_f32_e32 v5, 0x42400000, v119
	v_fmac_f32_e32 v23, 0x43d80000, v119
	v_cndmask_b32_e32 v2, v162, v2, vcc
	v_cndmask_b32_e64 v3, v162, v3, s[40:41]
	v_fmac_f32_e32 v6, 0x43000000, v119
	v_fmac_f32_e32 v7, 0x43100000, v119
	v_cndmask_b32_e64 v4, v162, v4, s[42:43]
	v_cndmask_b32_e64 v5, v162, v5, s[44:45]
	v_cndmask_b32_e64 v17, v162, v23, s[68:69]
	v_max3_f32 v23, v2, s88, v3
	v_fmac_f32_e32 v8, 0x43200000, v119
	v_fmac_f32_e32 v9, 0x43300000, v119
	v_cndmask_b32_e64 v6, v162, v6, s[46:47]
	v_cndmask_b32_e64 v7, v162, v7, s[48:49]
	v_max3_f32 v23, v23, v4, v5
	v_fmac_f32_e32 v10, 0x43800000, v119
	v_fmac_f32_e32 v11, 0x43880000, v119
	v_cndmask_b32_e64 v8, v162, v8, s[50:51]
	v_cndmask_b32_e64 v9, v162, v9, s[52:53]
	v_max3_f32 v23, v23, v6, v7
	v_fmac_f32_e32 v12, 0x43900000, v119
	v_fmac_f32_e32 v13, 0x43980000, v119
	v_cndmask_b32_e64 v10, v162, v10, s[54:55]
	v_cndmask_b32_e64 v11, v162, v11, s[56:57]
	v_max3_f32 v23, v23, v8, v9
	v_fmac_f32_e32 v14, 0x43c00000, v119
	v_fmac_f32_e32 v15, 0x43c80000, v119
	v_cndmask_b32_e64 v12, v162, v12, s[58:59]
	v_cndmask_b32_e64 v13, v162, v13, s[60:61]
	v_max3_f32 v23, v23, v10, v11
	v_fmac_f32_e32 v16, 0x43d00000, v119
	v_cndmask_b32_e64 v14, v162, v14, s[62:63]
	v_cndmask_b32_e64 v15, v162, v15, s[64:65]
	v_max3_f32 v23, v23, v12, v13
	v_cndmask_b32_e64 v16, v162, v16, s[66:67]
	v_max3_f32 v23, v23, v14, v15
	v_max3_f32 v23, v23, v16, v17
	ds_bpermute_b32 v24, v172, v23
	v_cmp_lt_f32_e32 vcc, s35, v2
	v_cmp_lt_f32_e64 s[40:41], s35, v3
	v_cmp_lt_f32_e64 s[42:43], s35, v4
	v_cmp_lt_f32_e64 s[44:45], s35, v5
	s_waitcnt lgkmcnt(0)
	v_max3_f32 v139, v22, v23, v24
	v_sub_f32_e32 v2, v2, v139
	v_sub_f32_e32 v3, v3, v139
	v_exp_f32_e32 v2, v2
	v_sub_f32_e32 v4, v4, v139
	v_exp_f32_e32 v3, v3
	v_sub_f32_e32 v5, v5, v139
	v_exp_f32_e32 v4, v4
	v_cmp_lt_f32_e64 s[46:47], s35, v6
	v_sub_f32_e32 v6, v6, v139
	v_exp_f32_e32 v5, v5
	v_cmp_lt_f32_e64 s[48:49], s35, v7
	v_sub_f32_e32 v7, v7, v139
	v_exp_f32_e32 v6, v6
	v_add_f32_e32 v2, 0, v2
	v_cmp_lt_f32_e64 s[50:51], s35, v8
	v_sub_f32_e32 v8, v8, v139
	v_exp_f32_e32 v7, v7
	v_cndmask_b32_e64 v3, 0, v3, s[40:41]
	v_cndmask_b32_e32 v2, 0, v2, vcc
	v_cmp_lt_f32_e64 s[52:53], s35, v9
	v_sub_f32_e32 v9, v9, v139
	v_exp_f32_e32 v8, v8
	v_cndmask_b32_e64 v4, 0, v4, s[42:43]
	v_add_f32_e32 v2, v3, v2
	v_cmp_lt_f32_e64 s[54:55], s35, v10
	v_sub_f32_e32 v10, v10, v139
	v_exp_f32_e32 v9, v9
	v_cndmask_b32_e64 v5, 0, v5, s[44:45]
	v_add_f32_e32 v2, v4, v2
	v_cmp_lt_f32_e64 s[56:57], s35, v11
	v_sub_f32_e32 v11, v11, v139
	v_exp_f32_e32 v10, v10
	v_cndmask_b32_e64 v6, 0, v6, s[46:47]
	v_add_f32_e32 v2, v5, v2
	v_cmp_lt_f32_e64 s[58:59], s35, v12
	v_sub_f32_e32 v12, v12, v139
	v_exp_f32_e32 v11, v11
	v_cndmask_b32_e64 v7, 0, v7, s[48:49]
	v_add_f32_e32 v2, v6, v2
	v_cmp_lt_f32_e64 s[60:61], s35, v13
	v_sub_f32_e32 v13, v13, v139
	v_exp_f32_e32 v12, v12
	v_cndmask_b32_e64 v8, 0, v8, s[50:51]
	v_add_f32_e32 v2, v7, v2
	v_cmp_lt_f32_e64 s[62:63], s35, v14
	v_sub_f32_e32 v14, v14, v139
	v_exp_f32_e32 v13, v13
	v_cndmask_b32_e64 v9, 0, v9, s[52:53]
	v_add_f32_e32 v2, v8, v2
	v_cmp_lt_f32_e64 s[64:65], s35, v15
	v_sub_f32_e32 v15, v15, v139
	v_exp_f32_e32 v14, v14
	v_cndmask_b32_e64 v10, 0, v10, s[54:55]
	v_add_f32_e32 v2, v9, v2
	v_cmp_lt_f32_e64 s[66:67], s35, v16
	v_sub_f32_e32 v16, v16, v139
	v_exp_f32_e32 v15, v15
	v_cndmask_b32_e64 v11, 0, v11, s[56:57]
	v_add_f32_e32 v2, v10, v2
	v_cmp_lt_f32_e64 s[68:69], s35, v17
	v_sub_f32_e32 v17, v17, v139
	v_exp_f32_e32 v16, v16
	v_cndmask_b32_e64 v12, 0, v12, s[58:59]
	v_add_f32_e32 v2, v11, v2
	v_exp_f32_e32 v17, v17
	v_cndmask_b32_e64 v13, 0, v13, s[60:61]
	v_add_f32_e32 v2, v12, v2
	v_sub_f32_e32 v22, v22, v139
	v_cndmask_b32_e64 v14, 0, v14, s[62:63]
	v_add_f32_e32 v2, v13, v2
	v_exp_f32_e32 v23, v22
	v_cndmask_b32_e64 v15, 0, v15, s[64:65]
	v_add_f32_e32 v2, v14, v2
	v_cndmask_b32_e64 v16, 0, v16, s[66:67]
	v_add_f32_e32 v2, v15, v2
	v_cndmask_b32_e64 v17, 0, v17, s[68:69]
	v_add_f32_e32 v2, v16, v2
	v_add_f32_e32 v22, v17, v2
	v_fmac_f32_e32 v22, v21, v23
	s_cbranch_scc1 .LBB0_309
	v_add_u32_e32 v145, 16, v122
	v_mad_u32_u24 v149, v173, s36, v145
	ds_read_b128 v[2:5], v149
	ds_read_b128 v[24:27], v149 offset:32
	v_sub_u32_e32 v20, v117, v0
	v_cvt_f32_i32_e32 v21, v20
	ds_bpermute_b32 v19, v172, v22
	s_waitcnt lgkmcnt(2)
	v_mfma_f32_32x32x16_bf16 v[2:17], v[2:5], v[82:85], 0
	v_sub_u32_e32 v66, v145, v18
	v_add_f32_e32 v21, 0xc1780000, v21
	v_fma_f32 v21, v21, -v119, -v139
	s_waitcnt lgkmcnt(0)
	v_add_f32_e32 v18, v22, v19
	v_rcp_f32_e32 v19, v18
	v_cmp_lt_f32_e32 vcc, 0, v18
	s_movk_i32 s25, 0x4e
	v_mfma_f32_32x32x16_bf16 v[2:17], v[24:27], v[86:89], v[2:17]
	ds_read_b128 v[24:27], v149 offset:64
	ds_read_b128 v[28:31], v149 offset:96
	v_cndmask_b32_e32 v123, 0, v19, vcc
	v_cmp_lt_i32_e32 vcc, 30, v20
	s_waitcnt lgkmcnt(1)
	v_mfma_f32_32x32x16_bf16 v[2:17], v[24:27], v[90:93], v[2:17]
	s_waitcnt lgkmcnt(0)
	v_mfma_f32_32x32x16_bf16 v[2:17], v[28:31], v[94:97], v[2:17]
	ds_read_b128 v[24:27], v149 offset:128
	ds_read_b128 v[28:31], v149 offset:160
	s_waitcnt lgkmcnt(1)
	v_mfma_f32_32x32x16_bf16 v[2:17], v[24:27], v[98:101], v[2:17]
	ds_read_b128 v[24:27], v149 offset:192
	s_waitcnt lgkmcnt(1)
	v_mfma_f32_32x32x16_bf16 v[2:17], v[28:31], v[102:105], v[2:17]
	ds_read_b128 v[28:31], v149 offset:224
	s_waitcnt lgkmcnt(1)
	v_mfma_f32_32x32x16_bf16 v[2:17], v[24:27], v[106:109], v[2:17]
	s_waitcnt lgkmcnt(0)
	v_mfma_f32_32x32x16_bf16 v[2:17], v[28:31], v[110:113], v[2:17]
	s_nop 11
	v_fmamk_f32 v2, v2, 0x3e0293ee, v21
	v_fmamk_f32 v3, v3, 0x3e0293ee, v21
	v_fmac_f32_e32 v2, 0, v119
	v_fmamk_f32 v4, v4, 0x3e0293ee, v21
	v_fmac_f32_e32 v3, 0x41800000, v119
	v_exp_f32_e32 v2, v2
	v_fmamk_f32 v5, v5, 0x3e0293ee, v21
	v_fmac_f32_e32 v4, 0x42000000, v119
	v_exp_f32_e32 v3, v3
	v_fmamk_f32 v6, v6, 0x3e0293ee, v21
	v_fmac_f32_e32 v5, 0x42400000, v119
	v_exp_f32_e32 v4, v4
	v_fmamk_f32 v7, v7, 0x3e0293ee, v21
	v_fmac_f32_e32 v6, 0x43000000, v119
	v_exp_f32_e32 v5, v5
	v_fmamk_f32 v8, v8, 0x3e0293ee, v21
	v_fmac_f32_e32 v7, 0x43100000, v119
	v_exp_f32_e32 v6, v6
	v_mul_f32_e32 v2, v123, v2
	v_fmamk_f32 v9, v9, 0x3e0293ee, v21
	v_fmac_f32_e32 v8, 0x43200000, v119
	v_exp_f32_e32 v7, v7
	v_mul_f32_e32 v3, v123, v3
	v_cndmask_b32_e32 v18, 0, v2, vcc
	v_cmp_lt_i32_e32 vcc, 46, v20
	v_fmamk_f32 v10, v10, 0x3e0293ee, v21
	v_fmac_f32_e32 v9, 0x43300000, v119
	v_exp_f32_e32 v8, v8
	v_mul_f32_e32 v4, v123, v4
	v_cndmask_b32_e32 v19, 0, v3, vcc
	v_cmp_lt_i32_e32 vcc, 62, v20
	v_fmamk_f32 v11, v11, 0x3e0293ee, v21
	v_fmac_f32_e32 v10, 0x43800000, v119
	v_exp_f32_e32 v9, v9
	v_mul_f32_e32 v5, v123, v5
	v_cndmask_b32_e32 v22, 0, v4, vcc
	v_cmp_lt_i32_e32 vcc, s25, v20
	v_fmac_f32_e32 v11, 0x43880000, v119
	v_exp_f32_e32 v10, v10
	v_mul_f32_e32 v6, v123, v6
	v_cndmask_b32_e32 v23, 0, v5, vcc
	v_cmp_lt_i32_e32 vcc, s28, v20
	v_exp_f32_e32 v11, v11
	v_mul_f32_e32 v7, v123, v7
	v_cndmask_b32_e32 v24, 0, v6, vcc
	v_cmp_lt_i32_e32 vcc, s29, v20
	v_mul_f32_e32 v8, v123, v8
	v_mul_f32_e32 v9, v123, v9
	v_cndmask_b32_e32 v25, 0, v7, vcc
	v_cmp_lt_i32_e32 vcc, s30, v20
	v_mul_f32_e32 v10, v123, v10
	v_mul_f32_e32 v2, v123, v11
	v_cndmask_b32_e32 v26, 0, v8, vcc
	v_cmp_lt_i32_e32 vcc, s31, v20
	v_fmamk_f32 v3, v13, 0x3e0293ee, v21
	v_fmac_f32_e32 v3, 0x43980000, v119
	v_cndmask_b32_e32 v9, 0, v9, vcc
	v_cmp_lt_i32_e32 vcc, s34, v20
	v_exp_f32_e32 v3, v3
	v_mul_f32_e32 v5, 0.5, v9
	v_cndmask_b32_e32 v67, 0, v10, vcc
	v_cmp_lt_i32_e32 vcc, s94, v20
	ds_bpermute_b32 v5, v172, v5
	s_nop 0
	v_cndmask_b32_e32 v68, 0, v2, vcc
	v_fmamk_f32 v2, v12, 0x3e0293ee, v21
	v_fmac_f32_e32 v2, 0x43900000, v119
	v_exp_f32_e32 v2, v2
	v_cmp_lt_i32_e32 vcc, s95, v20
	v_mul_f32_e32 v2, v123, v2
	s_nop 0
	v_cndmask_b32_e32 v69, 0, v2, vcc
	v_mul_f32_e32 v2, v123, v3
	v_cmp_lt_i32_e32 vcc, s73, v20
	v_fmamk_f32 v3, v15, 0x3e0293ee, v21
	v_fmac_f32_e32 v3, 0x43c80000, v119
	v_cndmask_b32_e32 v70, 0, v2, vcc
	v_fmamk_f32 v2, v14, 0x3e0293ee, v21
	v_fmac_f32_e32 v2, 0x43c00000, v119
	v_exp_f32_e32 v2, v2
	v_exp_f32_e32 v3, v3
	v_cmp_lt_i32_e32 vcc, s3, v20
	v_mul_f32_e32 v2, v123, v2
	s_nop 0
	v_cndmask_b32_e32 v71, 0, v2, vcc
	v_mul_f32_e32 v2, v123, v3
	v_cmp_lt_i32_e32 vcc, s89, v20
	s_nop 1
	v_cndmask_b32_e32 v72, 0, v2, vcc
	v_fmamk_f32 v2, v16, 0x3e0293ee, v21
	v_fmac_f32_e32 v2, 0x43d00000, v119
	v_fmac_f32_e32 v21, 0x3e0293ee, v17
	v_exp_f32_e32 v2, v2
	v_fmac_f32_e32 v21, 0x43d80000, v119
	v_exp_f32_e32 v3, v21
	v_cmp_lt_i32_e32 vcc, s1, v20
	v_mul_f32_e32 v2, v123, v2
	s_nop 0
	v_cndmask_b32_e32 v73, 0, v2, vcc
	v_mul_f32_e32 v2, v123, v3
	v_cmp_lt_i32_e32 vcc, s80, v20
	v_add_f32_e32 v3, v18, v19
	v_add_f32_e32 v3, v22, v3
	v_cndmask_b32_e32 v74, 0, v2, vcc
	v_mul_f32_e32 v2, 0.5, v23
	ds_bpermute_b32 v2, v172, v2
	v_cmp_eq_u32_e32 vcc, 0, v135
	v_fmac_f32_e32 v3, 0.5, v23
	s_waitcnt lgkmcnt(0)
	v_cndmask_b32_e64 v4, v2, 0, vcc
	v_add_f32_e32 v138, v4, v3
	v_mul_f32_e32 v4, 0.5, v70
	ds_bpermute_b32 v4, v172, v4
	v_add_f32_e32 v3, v24, v25
	v_add_f32_e32 v3, v26, v3
	v_fmac_f32_e32 v3, 0.5, v9
	v_cndmask_b32_e32 v2, v5, v2, vcc
	v_add_f32_e32 v137, v2, v3
	s_waitcnt lgkmcnt(0)
	v_cndmask_b32_e32 v3, v4, v5, vcc
	v_mul_f32_e32 v5, 0.5, v74
	v_add_f32_e32 v2, v67, v68
	ds_bpermute_b32 v140, v172, v5
	v_add_f32_e32 v2, v69, v2
	v_fmac_f32_e32 v2, 0.5, v70
	v_add_f32_e32 v136, v3, v2
	v_add_f32_e32 v2, v71, v72
	v_add_f32_e32 v2, v73, v2
	v_fmac_f32_e32 v2, 0.5, v74
	s_waitcnt lgkmcnt(0)
	v_cndmask_b32_e32 v3, v140, v4, vcc
	v_add_f32_e32 v133, v3, v2
	v_mad_u32_u24 v10, v173, s36, v66
	v_add_u32_e32 v144, 0x8800, v10
	ds_read2_b64 v[2:5], v144 offset1:2
	v_mad_u32_u24 v75, v173, s36, v163
	v_add_u32_e32 v11, v66, v75
	v_cvt_pk_bf16_f32 v6, v18, v19
	v_cvt_pk_bf16_f32 v7, v22, v23
	v_cvt_pk_bf16_f32 v8, v24, v25
	v_cvt_pk_bf16_f32 v9, v26, v9
	v_add_u32_e32 v141, 0x8800, v11
	v_add_u32_e32 v142, 0xc800, v10
	s_waitcnt lgkmcnt(0)
	v_mfma_f32_32x32x16_bf16 v[50:65], v[2:5], v[6:9], 0
	ds_read2_b64 v[2:5], v141 offset1:2
	v_mad_u32_u24 v153, v173, s36, v164
	s_waitcnt lgkmcnt(0)
	v_mfma_f32_32x32x16_bf16 v[34:49], v[2:5], v[6:9], 0
	ds_read2_b64 v[2:5], v142 offset0:128 offset1:130
	s_waitcnt lgkmcnt(0)
	v_mfma_f32_32x32x16_bf16 v[18:33], v[2:5], v[6:9], 0
	v_add_u32_e32 v2, v66, v153
	v_add_u32_e32 v143, 0x8800, v2
	ds_read2_b64 v[2:5], v143 offset1:2
	s_waitcnt lgkmcnt(0)
	v_mfma_f32_32x32x16_bf16 v[2:17], v[2:5], v[6:9], 0
	v_cvt_pk_bf16_f32 v66, v67, v68
	v_cvt_pk_bf16_f32 v67, v69, v70
	v_cvt_pk_bf16_f32 v68, v71, v72
	v_cvt_pk_bf16_f32 v69, v73, v74
	ds_read2_b64 v[70:73], v144 offset0:4 offset1:6
	ds_read2_b64 v[236:239], v141 offset0:4 offset1:6
	ds_read2_b64 v[240:243], v142 offset0:132 offset1:134
	ds_read2_b64 v[244:247], v143 offset0:4 offset1:6
	s_waitcnt lgkmcnt(3)
	v_mfma_f32_32x32x16_bf16 v[50:65], v[70:73], v[66:69], v[50:65]
	s_waitcnt lgkmcnt(2)
	v_mfma_f32_32x32x16_bf16 v[34:49], v[236:239], v[66:69], v[34:49]
	s_waitcnt lgkmcnt(1)
	v_mfma_f32_32x32x16_bf16 v[18:33], v[240:243], v[66:69], v[18:33]
	s_waitcnt lgkmcnt(0)
	v_mfma_f32_32x32x16_bf16 v[2:17], v[244:247], v[66:69], v[2:17]
	v_add_u32_e32 v146, v145, v75
	ds_read_b128 v[66:69], v146
	ds_read_b128 v[174:177], v146 offset:32
	ds_read_b128 v[212:215], v146 offset:64
	ds_read_b128 v[216:219], v146 offset:96
	ds_read_b128 v[220:223], v146 offset:128
	ds_read_b128 v[224:227], v146 offset:160
	ds_read_b128 v[228:231], v146 offset:192
	ds_read_b128 v[232:235], v146 offset:224
	s_waitcnt lgkmcnt(7)
	v_mfma_f32_32x32x16_bf16 v[66:81], v[66:69], v[82:85], 0
	s_waitcnt lgkmcnt(6)
	v_mfma_f32_32x32x16_bf16 v[66:81], v[174:177], v[86:89], v[66:81]
	s_waitcnt lgkmcnt(5)
	v_mfma_f32_32x32x16_bf16 v[66:81], v[212:215], v[90:93], v[66:81]
	s_waitcnt lgkmcnt(4)
	v_mfma_f32_32x32x16_bf16 v[66:81], v[216:219], v[94:97], v[66:81]
	s_waitcnt lgkmcnt(3)
	v_mfma_f32_32x32x16_bf16 v[66:81], v[220:223], v[98:101], v[66:81]
	s_waitcnt lgkmcnt(2)
	v_mfma_f32_32x32x16_bf16 v[66:81], v[224:227], v[102:105], v[66:81]
	s_waitcnt lgkmcnt(1)
	v_mfma_f32_32x32x16_bf16 v[66:81], v[228:231], v[106:109], v[66:81]
	v_or_b32_e32 v146, 0x200, v0
	v_sub_u32_e32 v146, v117, v146
	v_cvt_f32_i32_e32 v147, v146
	v_cmp_lt_i32_e64 s[40:41], 30, v146
	v_add_f32_e32 v147, 0xc1780000, v147
	s_waitcnt lgkmcnt(0)
	v_mfma_f32_32x32x16_bf16 v[66:81], v[232:235], v[110:113], v[66:81]
	v_fma_f32 v147, v147, -v119, -v139
	s_nop 10
	v_fmamk_f32 v66, v66, 0x3e0293ee, v147
	v_fmac_f32_e32 v66, 0, v119
	v_fmamk_f32 v67, v67, 0x3e0293ee, v147
	v_exp_f32_e32 v66, v66
	v_fmac_f32_e32 v67, 0x41800000, v119
	v_fmamk_f32 v68, v68, 0x3e0293ee, v147
	v_exp_f32_e32 v67, v67
	v_fmac_f32_e32 v68, 0x42000000, v119
	v_fmamk_f32 v69, v69, 0x3e0293ee, v147
	v_exp_f32_e32 v68, v68
	v_fmac_f32_e32 v69, 0x42400000, v119
	v_fmamk_f32 v70, v70, 0x3e0293ee, v147
	v_exp_f32_e32 v69, v69
	v_fmac_f32_e32 v70, 0x43000000, v119
	v_fmamk_f32 v71, v71, 0x3e0293ee, v147
	v_mul_f32_e32 v66, v123, v66
	v_exp_f32_e32 v70, v70
	v_fmac_f32_e32 v71, 0x43100000, v119
	v_fmamk_f32 v72, v72, 0x3e0293ee, v147
	v_cndmask_b32_e64 v66, 0, v66, s[40:41]
	v_mul_f32_e32 v67, v123, v67
	v_cmp_lt_i32_e64 s[40:41], 46, v146
	v_exp_f32_e32 v71, v71
	v_fmac_f32_e32 v72, 0x43200000, v119
	v_fmamk_f32 v73, v73, 0x3e0293ee, v147
	v_cndmask_b32_e64 v67, 0, v67, s[40:41]
	v_mul_f32_e32 v68, v123, v68
	v_cmp_lt_i32_e64 s[40:41], 62, v146
	v_exp_f32_e32 v72, v72
	v_fmac_f32_e32 v73, 0x43300000, v119
	v_fmamk_f32 v74, v74, 0x3e0293ee, v147
	v_cndmask_b32_e64 v68, 0, v68, s[40:41]
	v_mul_f32_e32 v69, v123, v69
	v_cmp_lt_i32_e64 s[40:41], s25, v146
	v_exp_f32_e32 v73, v73
	v_fmac_f32_e32 v74, 0x43800000, v119
	v_fmamk_f32 v75, v75, 0x3e0293ee, v147
	v_cndmask_b32_e64 v69, 0, v69, s[40:41]
	v_mul_f32_e32 v70, v123, v70
	v_cmp_lt_i32_e64 s[40:41], s28, v146
	v_exp_f32_e32 v74, v74
	v_fmac_f32_e32 v75, 0x43880000, v119
	v_fmamk_f32 v76, v76, 0x3e0293ee, v147
	v_cndmask_b32_e64 v70, 0, v70, s[40:41]
	v_mul_f32_e32 v71, v123, v71
	v_cmp_lt_i32_e64 s[40:41], s29, v146
	v_exp_f32_e32 v75, v75
	v_fmac_f32_e32 v76, 0x43900000, v119
	v_fmamk_f32 v77, v77, 0x3e0293ee, v147
	v_cndmask_b32_e64 v71, 0, v71, s[40:41]
	v_mul_f32_e32 v72, v123, v72
	v_cmp_lt_i32_e64 s[40:41], s30, v146
	v_exp_f32_e32 v76, v76
	v_fmac_f32_e32 v77, 0x43980000, v119
	v_fmamk_f32 v78, v78, 0x3e0293ee, v147
	v_cndmask_b32_e64 v72, 0, v72, s[40:41]
	v_mul_f32_e32 v73, v123, v73
	v_cmp_lt_i32_e64 s[40:41], s31, v146
	v_exp_f32_e32 v77, v77
	v_fmac_f32_e32 v78, 0x43c00000, v119
	v_fmamk_f32 v79, v79, 0x3e0293ee, v147
	v_cndmask_b32_e64 v73, 0, v73, s[40:41]
	v_mul_f32_e32 v74, v123, v74
	v_cmp_lt_i32_e64 s[40:41], s34, v146
	v_exp_f32_e32 v78, v78
	v_fmac_f32_e32 v79, 0x43c80000, v119
	v_fmamk_f32 v80, v80, 0x3e0293ee, v147
	v_cndmask_b32_e64 v74, 0, v74, s[40:41]
	v_mul_f32_e32 v75, v123, v75
	v_cmp_lt_i32_e64 s[40:41], s94, v146
	v_exp_f32_e32 v79, v79
	v_fmac_f32_e32 v80, 0x43d00000, v119
	v_cndmask_b32_e64 v75, 0, v75, s[40:41]
	v_mul_f32_e32 v76, v123, v76
	v_cmp_lt_i32_e64 s[40:41], s95, v146
	v_exp_f32_e32 v80, v80
	v_mul_f32_e32 v77, v123, v77
	v_cndmask_b32_e64 v76, 0, v76, s[40:41]
	v_cmp_lt_i32_e64 s[40:41], s73, v146
	v_mul_f32_e32 v78, v123, v78
	v_mul_f32_e32 v79, v123, v79
	v_cndmask_b32_e64 v77, 0, v77, s[40:41]
	v_cmp_lt_i32_e64 s[40:41], s3, v146
	v_mul_f32_e32 v80, v123, v80
	v_fmac_f32_e32 v147, 0x3e0293ee, v81
	v_cndmask_b32_e64 v78, 0, v78, s[40:41]
	v_cmp_lt_i32_e64 s[40:41], s89, v146
	v_fmac_f32_e32 v147, 0x43d80000, v119
	v_exp_f32_e32 v81, v147
	v_cndmask_b32_e64 v79, 0, v79, s[40:41]
	v_cmp_lt_i32_e64 s[40:41], s1, v146
	v_add_f32_e32 v147, v66, v67
	v_add_f32_e32 v147, v68, v147
	v_cndmask_b32_e64 v80, 0, v80, s[40:41]
	v_cmp_lt_i32_e64 s[40:41], s80, v146
	v_mul_f32_e32 v146, 0.5, v69
	ds_bpermute_b32 v146, v172, v146
	v_fmac_f32_e32 v147, 0.5, v69
	v_add_f32_e32 v148, v70, v71
	v_add_f32_e32 v148, v72, v148
	v_fmac_f32_e32 v148, 0.5, v73
	s_waitcnt lgkmcnt(0)
	v_cndmask_b32_e32 v140, v146, v140, vcc
	v_add_f32_e32 v147, v140, v147
	v_mul_f32_e32 v140, 0.5, v73
	ds_bpermute_b32 v140, v172, v140
	v_mul_f32_e32 v81, v123, v81
	v_cndmask_b32_e64 v81, 0, v81, s[40:41]
	s_waitcnt lgkmcnt(0)
	v_cndmask_b32_e32 v146, v140, v146, vcc
	v_add_f32_e32 v148, v146, v148
	v_mul_f32_e32 v146, 0.5, v77
	ds_bpermute_b32 v150, v172, v146
	v_add_f32_e32 v146, v74, v75
	v_add_f32_e32 v146, v76, v146
	v_fmac_f32_e32 v146, 0.5, v77
	s_waitcnt lgkmcnt(0)
	v_cndmask_b32_e32 v140, v150, v140, vcc
	v_add_f32_e32 v146, v140, v146
	v_mul_f32_e32 v140, 0.5, v81
	ds_bpermute_b32 v151, v172, v140
	v_add_f32_e32 v140, v78, v79
	v_add_f32_e32 v140, v80, v140
	v_fmac_f32_e32 v140, 0.5, v81
	s_waitcnt lgkmcnt(0)
	v_cndmask_b32_e32 v150, v151, v150, vcc
	v_add_f32_e32 v140, v150, v140
	v_cvt_pk_bf16_f32 v66, v66, v67
	v_cvt_pk_bf16_f32 v67, v68, v69
	v_cvt_pk_bf16_f32 v68, v70, v71
	v_cvt_pk_bf16_f32 v69, v72, v73
	ds_read2_b64 v[70:73], v144 offset0:8 offset1:10
	ds_read2_b64 v[236:239], v141 offset0:8 offset1:10
	ds_read2_b64 v[240:243], v142 offset0:136 offset1:138
	ds_read2_b64 v[244:247], v143 offset0:8 offset1:10
	s_waitcnt lgkmcnt(3)
	v_mfma_f32_32x32x16_bf16 v[50:65], v[70:73], v[66:69], v[50:65]
	s_waitcnt lgkmcnt(2)
	v_mfma_f32_32x32x16_bf16 v[34:49], v[236:239], v[66:69], v[34:49]
	s_waitcnt lgkmcnt(1)
	v_mfma_f32_32x32x16_bf16 v[18:33], v[240:243], v[66:69], v[18:33]
	s_waitcnt lgkmcnt(0)
	v_mfma_f32_32x32x16_bf16 v[2:17], v[244:247], v[66:69], v[2:17]
	ds_read2_b64 v[70:73], v144 offset0:12 offset1:14
	ds_read2_b64 v[236:239], v141 offset0:12 offset1:14
	ds_read2_b64 v[240:243], v142 offset0:140 offset1:142
	ds_read2_b64 v[244:247], v143 offset0:12 offset1:14
	v_cvt_pk_bf16_f32 v66, v74, v75
	v_cvt_pk_bf16_f32 v67, v76, v77
	v_cvt_pk_bf16_f32 v68, v78, v79
	v_cvt_pk_bf16_f32 v69, v80, v81
	s_waitcnt lgkmcnt(3)
	s_nop 0
	v_mfma_f32_32x32x16_bf16 v[50:65], v[70:73], v[66:69], v[50:65]
	s_waitcnt lgkmcnt(2)
	v_mfma_f32_32x32x16_bf16 v[34:49], v[236:239], v[66:69], v[34:49]
	s_waitcnt lgkmcnt(1)
	v_mfma_f32_32x32x16_bf16 v[18:33], v[240:243], v[66:69], v[18:33]
	s_waitcnt lgkmcnt(0)
	v_mfma_f32_32x32x16_bf16 v[2:17], v[244:247], v[66:69], v[2:17]
	ds_read_b128 v[66:69], v149 offset:17408
	ds_read_b128 v[174:177], v149 offset:17440
	s_waitcnt lgkmcnt(1)
	v_mfma_f32_32x32x16_bf16 v[66:81], v[66:69], v[82:85], 0
	s_waitcnt lgkmcnt(0)
	v_mfma_f32_32x32x16_bf16 v[66:81], v[174:177], v[86:89], v[66:81]
	ds_read_b128 v[174:177], v149 offset:17472
	ds_read_b128 v[178:181], v149 offset:17504
	s_waitcnt lgkmcnt(1)
	v_mfma_f32_32x32x16_bf16 v[66:81], v[174:177], v[90:93], v[66:81]
	s_waitcnt lgkmcnt(0)
	v_mfma_f32_32x32x16_bf16 v[66:81], v[178:181], v[94:97], v[66:81]
	ds_read_b128 v[174:177], v149 offset:17536
	ds_read_b128 v[178:181], v149 offset:17568
	s_waitcnt lgkmcnt(1)
	v_mfma_f32_32x32x16_bf16 v[66:81], v[174:177], v[98:101], v[66:81]
	s_waitcnt lgkmcnt(0)
	v_mfma_f32_32x32x16_bf16 v[66:81], v[178:181], v[102:105], v[66:81]
	ds_read_b128 v[174:177], v149 offset:17600
	ds_read_b128 v[178:181], v149 offset:17632
	v_or_b32_e32 v149, 0x400, v0
	v_sub_u32_e32 v149, v117, v149
	v_cvt_f32_i32_e32 v150, v149
	v_cmp_lt_i32_e64 s[40:41], 30, v149
	v_add_f32_e32 v150, 0xc1780000, v150
	s_waitcnt lgkmcnt(1)
	v_mfma_f32_32x32x16_bf16 v[66:81], v[174:177], v[106:109], v[66:81]
	v_fma_f32 v150, v150, -v119, -v139
	s_waitcnt lgkmcnt(0)
	v_mfma_f32_32x32x16_bf16 v[66:81], v[178:181], v[110:113], v[66:81]
	s_nop 11
	v_fmamk_f32 v66, v66, 0x3e0293ee, v150
	v_fmamk_f32 v67, v67, 0x3e0293ee, v150
	v_fmac_f32_e32 v66, 0, v119
	v_fmamk_f32 v68, v68, 0x3e0293ee, v150
	v_fmac_f32_e32 v67, 0x41800000, v119
	v_exp_f32_e32 v66, v66
	v_fmamk_f32 v69, v69, 0x3e0293ee, v150
	v_fmac_f32_e32 v68, 0x42000000, v119
	v_exp_f32_e32 v67, v67
	v_fmamk_f32 v70, v70, 0x3e0293ee, v150
	v_fmac_f32_e32 v69, 0x42400000, v119
	v_exp_f32_e32 v68, v68
	v_fmamk_f32 v71, v71, 0x3e0293ee, v150
	v_fmac_f32_e32 v70, 0x43000000, v119
	v_exp_f32_e32 v69, v69
	v_fmamk_f32 v72, v72, 0x3e0293ee, v150
	v_fmac_f32_e32 v71, 0x43100000, v119
	v_exp_f32_e32 v70, v70
	v_mul_f32_e32 v66, v123, v66
	v_fmamk_f32 v73, v73, 0x3e0293ee, v150
	v_fmac_f32_e32 v72, 0x43200000, v119
	v_exp_f32_e32 v71, v71
	v_mul_f32_e32 v67, v123, v67
	v_cndmask_b32_e64 v66, 0, v66, s[40:41]
	v_cmp_lt_i32_e64 s[40:41], 46, v149
	v_fmamk_f32 v74, v74, 0x3e0293ee, v150
	v_fmac_f32_e32 v73, 0x43300000, v119
	v_exp_f32_e32 v72, v72
	v_mul_f32_e32 v68, v123, v68
	v_cndmask_b32_e64 v67, 0, v67, s[40:41]
	v_cmp_lt_i32_e64 s[40:41], 62, v149
	v_fmamk_f32 v75, v75, 0x3e0293ee, v150
	v_fmac_f32_e32 v74, 0x43800000, v119
	v_exp_f32_e32 v73, v73
	v_mul_f32_e32 v69, v123, v69
	v_cndmask_b32_e64 v68, 0, v68, s[40:41]
	v_cmp_lt_i32_e64 s[40:41], s25, v149
	v_fmac_f32_e32 v75, 0x43880000, v119
	v_exp_f32_e32 v74, v74
	v_mul_f32_e32 v70, v123, v70
	v_cndmask_b32_e64 v69, 0, v69, s[40:41]
	v_cmp_lt_i32_e64 s[40:41], s28, v149
	v_fmamk_f32 v76, v76, 0x3e0293ee, v150
	v_exp_f32_e32 v75, v75
	v_mul_f32_e32 v71, v123, v71
	v_cndmask_b32_e64 v70, 0, v70, s[40:41]
	v_cmp_lt_i32_e64 s[40:41], s29, v149
	v_fmac_f32_e32 v76, 0x43900000, v119
	v_fmamk_f32 v77, v77, 0x3e0293ee, v150
	v_mul_f32_e32 v72, v123, v72
	v_cndmask_b32_e64 v71, 0, v71, s[40:41]
	v_cmp_lt_i32_e64 s[40:41], s30, v149
	v_exp_f32_e32 v76, v76
	v_fmac_f32_e32 v77, 0x43980000, v119
	v_fmamk_f32 v78, v78, 0x3e0293ee, v150
	v_mul_f32_e32 v73, v123, v73
	v_cndmask_b32_e64 v72, 0, v72, s[40:41]
	v_cmp_lt_i32_e64 s[40:41], s31, v149
	v_exp_f32_e32 v77, v77
	v_fmac_f32_e32 v78, 0x43c00000, v119
	v_fmamk_f32 v79, v79, 0x3e0293ee, v150
	v_mul_f32_e32 v74, v123, v74
	v_cndmask_b32_e64 v73, 0, v73, s[40:41]
	v_cmp_lt_i32_e64 s[40:41], s34, v149
	v_exp_f32_e32 v78, v78
	v_fmac_f32_e32 v79, 0x43c80000, v119
	v_fmamk_f32 v80, v80, 0x3e0293ee, v150
	v_mul_f32_e32 v75, v123, v75
	v_cndmask_b32_e64 v74, 0, v74, s[40:41]
	v_cmp_lt_i32_e64 s[40:41], s94, v149
	v_exp_f32_e32 v79, v79
	v_fmac_f32_e32 v80, 0x43d00000, v119
	v_fmac_f32_e32 v150, 0x3e0293ee, v81
	v_cndmask_b32_e64 v75, 0, v75, s[40:41]
	v_mul_f32_e32 v76, v123, v76
	v_cmp_lt_i32_e64 s[40:41], s95, v149
	v_exp_f32_e32 v80, v80
	v_fmac_f32_e32 v150, 0x43d80000, v119
	v_cndmask_b32_e64 v76, 0, v76, s[40:41]
	v_mul_f32_e32 v77, v123, v77
	v_cmp_lt_i32_e64 s[40:41], s73, v149
	v_exp_f32_e32 v81, v150
	v_mul_f32_e32 v150, 0.5, v69
	v_cndmask_b32_e64 v77, 0, v77, s[40:41]
	v_mul_f32_e32 v78, v123, v78
	v_cmp_lt_i32_e64 s[40:41], s3, v149
	ds_bpermute_b32 v150, v172, v150
	v_mul_f32_e32 v79, v123, v79
	v_cndmask_b32_e64 v78, 0, v78, s[40:41]
	v_cmp_lt_i32_e64 s[40:41], s89, v149
	v_mul_f32_e32 v80, v123, v80
	s_waitcnt lgkmcnt(0)
	v_cndmask_b32_e32 v151, v150, v151, vcc
	v_cndmask_b32_e64 v79, 0, v79, s[40:41]
	v_cmp_lt_i32_e64 s[40:41], s1, v149
	v_mul_f32_e32 v152, 0.5, v73
	ds_bpermute_b32 v154, v172, v152
	v_cndmask_b32_e64 v80, 0, v80, s[40:41]
	v_cmp_lt_i32_e64 s[40:41], s80, v149
	v_add_f32_e32 v149, v66, v67
	v_add_f32_e32 v149, v68, v149
	v_fmac_f32_e32 v149, 0.5, v69
	v_add_f32_e32 v152, v151, v149
	v_mul_f32_e32 v151, 0.5, v77
	ds_bpermute_b32 v155, v172, v151
	v_add_f32_e32 v149, v70, v71
	v_mul_f32_e32 v81, v123, v81
	v_add_f32_e32 v149, v72, v149
	v_cndmask_b32_e64 v81, 0, v81, s[40:41]
	v_fmac_f32_e32 v149, 0.5, v73
	s_waitcnt lgkmcnt(1)
	v_cndmask_b32_e32 v150, v154, v150, vcc
	v_add_f32_e32 v151, v150, v149
	s_waitcnt lgkmcnt(0)
	v_cndmask_b32_e32 v150, v155, v154, vcc
	v_mul_f32_e32 v154, 0.5, v81
	v_add_f32_e32 v149, v74, v75
	ds_bpermute_b32 v154, v172, v154
	v_add_f32_e32 v149, v76, v149
	v_fmac_f32_e32 v149, 0.5, v77
	v_add_f32_e32 v150, v150, v149
	v_add_f32_e32 v149, v78, v79
	v_add_f32_e32 v149, v80, v149
	v_fmac_f32_e32 v149, 0.5, v81
	s_waitcnt lgkmcnt(0)
	v_cndmask_b32_e32 v155, v154, v155, vcc
	v_add_f32_e32 v149, v155, v149
	v_cvt_pk_bf16_f32 v66, v66, v67
	v_cvt_pk_bf16_f32 v67, v68, v69
	v_cvt_pk_bf16_f32 v68, v70, v71
	v_cvt_pk_bf16_f32 v69, v72, v73
	ds_read2_b64 v[70:73], v144 offset0:16 offset1:18
	ds_read2_b64 v[236:239], v141 offset0:16 offset1:18
	ds_read2_b64 v[240:243], v142 offset0:144 offset1:146
	ds_read2_b64 v[244:247], v143 offset0:16 offset1:18
	s_waitcnt lgkmcnt(3)
	v_mfma_f32_32x32x16_bf16 v[50:65], v[70:73], v[66:69], v[50:65]
	s_waitcnt lgkmcnt(2)
	v_mfma_f32_32x32x16_bf16 v[34:49], v[236:239], v[66:69], v[34:49]
	s_waitcnt lgkmcnt(1)
	v_mfma_f32_32x32x16_bf16 v[18:33], v[240:243], v[66:69], v[18:33]
	s_waitcnt lgkmcnt(0)
	v_mfma_f32_32x32x16_bf16 v[2:17], v[244:247], v[66:69], v[2:17]
	ds_read2_b64 v[70:73], v144 offset0:20 offset1:22
	ds_read2_b64 v[236:239], v141 offset0:20 offset1:22
	ds_read2_b64 v[240:243], v142 offset0:148 offset1:150
	ds_read2_b64 v[244:247], v143 offset0:20 offset1:22
	v_cvt_pk_bf16_f32 v66, v74, v75
	v_cvt_pk_bf16_f32 v67, v76, v77
	v_cvt_pk_bf16_f32 v68, v78, v79
	v_cvt_pk_bf16_f32 v69, v80, v81
	s_waitcnt lgkmcnt(3)
	s_nop 0
	v_mfma_f32_32x32x16_bf16 v[50:65], v[70:73], v[66:69], v[50:65]
	s_waitcnt lgkmcnt(2)
	v_mfma_f32_32x32x16_bf16 v[34:49], v[236:239], v[66:69], v[34:49]
	s_waitcnt lgkmcnt(1)
	v_mfma_f32_32x32x16_bf16 v[18:33], v[240:243], v[66:69], v[18:33]
	s_waitcnt lgkmcnt(0)
	v_mfma_f32_32x32x16_bf16 v[2:17], v[244:247], v[66:69], v[2:17]
	v_add_u32_e32 v145, v145, v153
	ds_read_b128 v[66:69], v145
	ds_read_b128 v[174:177], v145 offset:32
	v_or_b32_e32 v0, 0x600, v0
	v_sub_u32_e32 v0, v117, v0
	v_cmp_lt_i32_e64 s[40:41], 30, v0
	s_waitcnt lgkmcnt(1)
	v_mfma_f32_32x32x16_bf16 v[66:81], v[66:69], v[82:85], 0
	s_waitcnt lgkmcnt(0)
	v_mfma_f32_32x32x16_bf16 v[66:81], v[174:177], v[86:89], v[66:81]
	ds_read_b128 v[174:177], v145 offset:64
	ds_read_b128 v[178:181], v145 offset:96
	s_waitcnt lgkmcnt(1)
	v_mfma_f32_32x32x16_bf16 v[66:81], v[174:177], v[90:93], v[66:81]
	s_waitcnt lgkmcnt(0)
	v_mfma_f32_32x32x16_bf16 v[66:81], v[178:181], v[94:97], v[66:81]
	ds_read_b128 v[174:177], v145 offset:128
	ds_read_b128 v[178:181], v145 offset:160
	s_waitcnt lgkmcnt(1)
	v_mfma_f32_32x32x16_bf16 v[66:81], v[174:177], v[98:101], v[66:81]
	ds_read_b128 v[174:177], v145 offset:192
	s_waitcnt lgkmcnt(1)
	v_mfma_f32_32x32x16_bf16 v[66:81], v[178:181], v[102:105], v[66:81]
	ds_read_b128 v[178:181], v145 offset:224
	v_cvt_f32_i32_e32 v145, v0
	v_add_f32_e32 v145, 0xc1780000, v145
	v_fma_f32 v139, v145, -v119, -v139
	s_waitcnt lgkmcnt(1)
	v_mfma_f32_32x32x16_bf16 v[66:81], v[174:177], v[106:109], v[66:81]
	s_waitcnt lgkmcnt(0)
	v_mfma_f32_32x32x16_bf16 v[66:81], v[178:181], v[110:113], v[66:81]
	s_nop 11
	v_fmamk_f32 v66, v66, 0x3e0293ee, v139
	v_fmamk_f32 v67, v67, 0x3e0293ee, v139
	v_fmac_f32_e32 v66, 0, v119
	v_fmamk_f32 v68, v68, 0x3e0293ee, v139
	v_fmac_f32_e32 v67, 0x41800000, v119
	v_exp_f32_e32 v66, v66
	v_fmamk_f32 v69, v69, 0x3e0293ee, v139
	v_fmac_f32_e32 v68, 0x42000000, v119
	v_exp_f32_e32 v67, v67
	v_fmamk_f32 v70, v70, 0x3e0293ee, v139
	v_fmac_f32_e32 v69, 0x42400000, v119
	v_exp_f32_e32 v68, v68
	v_fmamk_f32 v71, v71, 0x3e0293ee, v139
	v_fmac_f32_e32 v70, 0x43000000, v119
	v_exp_f32_e32 v69, v69
	v_fmamk_f32 v72, v72, 0x3e0293ee, v139
	v_fmac_f32_e32 v71, 0x43100000, v119
	v_exp_f32_e32 v70, v70
	v_mul_f32_e32 v66, v123, v66
	v_fmamk_f32 v73, v73, 0x3e0293ee, v139
	v_fmac_f32_e32 v72, 0x43200000, v119
	v_exp_f32_e32 v71, v71
	v_mul_f32_e32 v67, v123, v67
	v_cndmask_b32_e64 v66, 0, v66, s[40:41]
	v_cmp_lt_i32_e64 s[40:41], 46, v0
	v_fmamk_f32 v74, v74, 0x3e0293ee, v139
	v_fmac_f32_e32 v73, 0x43300000, v119
	v_exp_f32_e32 v72, v72
	v_mul_f32_e32 v68, v123, v68
	v_cndmask_b32_e64 v67, 0, v67, s[40:41]
	v_cmp_lt_i32_e64 s[40:41], 62, v0
	v_fmamk_f32 v75, v75, 0x3e0293ee, v139
	v_fmac_f32_e32 v74, 0x43800000, v119
	v_exp_f32_e32 v73, v73
	v_mul_f32_e32 v69, v123, v69
	v_cndmask_b32_e64 v145, 0, v68, s[40:41]
	v_cmp_lt_i32_e64 s[40:41], s25, v0
	v_fmac_f32_e32 v75, 0x43880000, v119
	v_exp_f32_e32 v74, v74
	v_mul_f32_e32 v70, v123, v70
	v_cndmask_b32_e64 v153, 0, v69, s[40:41]
	v_cmp_lt_i32_e64 s[40:41], s28, v0
	v_fmamk_f32 v68, v76, 0x3e0293ee, v139
	v_exp_f32_e32 v75, v75
	v_mul_f32_e32 v71, v123, v71
	v_cndmask_b32_e64 v155, 0, v70, s[40:41]
	v_cmp_lt_i32_e64 s[40:41], s29, v0
	v_fmac_f32_e32 v68, 0x43900000, v119
	v_fmamk_f32 v69, v77, 0x3e0293ee, v139
	v_mul_f32_e32 v72, v123, v72
	v_cndmask_b32_e64 v174, 0, v71, s[40:41]
	v_cmp_lt_i32_e64 s[40:41], s30, v0
	v_exp_f32_e32 v68, v68
	v_fmac_f32_e32 v69, 0x43980000, v119
	v_mul_f32_e32 v73, v123, v73
	v_cndmask_b32_e64 v175, 0, v72, s[40:41]
	v_cmp_lt_i32_e64 s[40:41], s31, v0
	v_exp_f32_e32 v69, v69
	v_mul_f32_e32 v74, v123, v74
	v_cndmask_b32_e64 v176, 0, v73, s[40:41]
	v_cmp_lt_i32_e64 s[40:41], s34, v0
	v_mul_f32_e32 v75, v123, v75
	v_mul_f32_e32 v68, v123, v68
	v_cndmask_b32_e64 v177, 0, v74, s[40:41]
	v_cmp_lt_i32_e64 s[40:41], s94, v0
	v_mul_f32_e32 v71, 0.5, v176
	ds_bpermute_b32 v72, v172, v71
	v_cndmask_b32_e64 v178, 0, v75, s[40:41]
	v_cmp_lt_i32_e64 s[40:41], s95, v0
	s_nop 1
	v_cndmask_b32_e64 v179, 0, v68, s[40:41]
	v_mul_f32_e32 v68, v123, v69
	v_cmp_lt_i32_e64 s[40:41], s73, v0
	v_fmamk_f32 v69, v79, 0x3e0293ee, v139
	v_fmac_f32_e32 v69, 0x43c80000, v119
	v_cndmask_b32_e64 v180, 0, v68, s[40:41]
	v_fmamk_f32 v68, v78, 0x3e0293ee, v139
	v_fmac_f32_e32 v68, 0x43c00000, v119
	v_exp_f32_e32 v68, v68
	v_exp_f32_e32 v69, v69
	v_cmp_lt_i32_e64 s[40:41], s3, v0
	v_mul_f32_e32 v68, v123, v68
	s_nop 0
	v_cndmask_b32_e64 v181, 0, v68, s[40:41]
	v_mul_f32_e32 v68, v123, v69
	v_cmp_lt_i32_e64 s[40:41], s89, v0
	s_nop 1
	v_cndmask_b32_e64 v182, 0, v68, s[40:41]
	v_fmamk_f32 v68, v80, 0x3e0293ee, v139
	v_fmac_f32_e32 v68, 0x43d00000, v119
	v_fmac_f32_e32 v139, 0x3e0293ee, v81
	v_exp_f32_e32 v68, v68
	v_fmac_f32_e32 v139, 0x43d80000, v119
	v_exp_f32_e32 v69, v139
	v_cmp_lt_i32_e64 s[40:41], s1, v0
	v_mul_f32_e32 v68, v123, v68
	s_nop 0
	v_cndmask_b32_e64 v80, 0, v68, s[40:41]
	v_mul_f32_e32 v68, v123, v69
	v_mul_f32_e32 v69, 0.5, v153
	ds_bpermute_b32 v69, v172, v69
	v_cmp_lt_i32_e64 s[40:41], s80, v0
	s_waitcnt lgkmcnt(0)
	v_cndmask_b32_e32 v70, v69, v154, vcc
	v_cndmask_b32_e64 v0, 0, v68, s[40:41]
	v_add_f32_e32 v68, v66, v67
	v_add_f32_e32 v68, v145, v68
	v_fmac_f32_e32 v68, 0.5, v153
	v_add_f32_e32 v71, v70, v68
	v_mul_f32_e32 v70, 0.5, v180
	ds_bpermute_b32 v73, v172, v70
	v_add_f32_e32 v68, v155, v174
	v_add_f32_e32 v68, v175, v68
	v_fmac_f32_e32 v68, 0.5, v176
	v_cndmask_b32_e32 v69, v72, v69, vcc
	v_add_f32_e32 v70, v69, v68
	s_waitcnt lgkmcnt(0)
	v_cndmask_b32_e32 v69, v73, v72, vcc
	v_mul_f32_e32 v72, 0.5, v0
	v_add_f32_e32 v68, v177, v178
	ds_bpermute_b32 v72, v172, v72
	v_add_f32_e32 v68, v179, v68
	v_fmac_f32_e32 v68, 0.5, v180
	v_add_f32_e32 v69, v69, v68
	v_add_f32_e32 v68, v181, v182
	v_add_f32_e32 v68, v80, v68
	v_fmac_f32_e32 v68, 0.5, v0
	s_waitcnt lgkmcnt(0)
	v_cndmask_b32_e32 v72, v72, v73, vcc
	v_add_f32_e32 v68, v72, v68
	ds_read2_b64 v[76:79], v144 offset0:24 offset1:26
	ds_read2_b64 v[236:239], v141 offset0:24 offset1:26
	ds_read2_b64 v[240:243], v142 offset0:152 offset1:154
	ds_read2_b64 v[244:247], v143 offset0:24 offset1:26
	v_cvt_pk_bf16_f32 v72, v66, v67
	v_cvt_pk_bf16_f32 v73, v145, v153
	v_cvt_pk_bf16_f32 v74, v155, v174
	v_cvt_pk_bf16_f32 v75, v175, v176
	s_waitcnt lgkmcnt(3)
	s_nop 0
	v_mfma_f32_32x32x16_bf16 v[50:65], v[76:79], v[72:75], v[50:65]
	s_waitcnt lgkmcnt(2)
	v_mfma_f32_32x32x16_bf16 v[34:49], v[236:239], v[72:75], v[34:49]
	s_waitcnt lgkmcnt(1)
	v_mfma_f32_32x32x16_bf16 v[18:33], v[240:243], v[72:75], v[18:33]
	s_waitcnt lgkmcnt(0)
	v_mfma_f32_32x32x16_bf16 v[2:17], v[244:247], v[72:75], v[2:17]
	ds_read2_b64 v[76:79], v144 offset0:28 offset1:30
	ds_read2_b64 v[236:239], v141 offset0:28 offset1:30
	ds_read2_b64 v[240:243], v142 offset0:156 offset1:158
	ds_read2_b64 v[244:247], v143 offset0:28 offset1:30
	v_cvt_pk_bf16_f32 v72, v177, v178
	v_cvt_pk_bf16_f32 v73, v179, v180
	v_cvt_pk_bf16_f32 v74, v181, v182
	v_cvt_pk_bf16_f32 v75, v80, v0
	s_waitcnt lgkmcnt(3)
	s_nop 0
	v_mfma_f32_32x32x16_bf16 v[50:65], v[76:79], v[72:75], v[50:65]
	s_waitcnt lgkmcnt(2)
	v_mfma_f32_32x32x16_bf16 v[34:49], v[236:239], v[72:75], v[34:49]
	s_waitcnt lgkmcnt(1)
	v_mfma_f32_32x32x16_bf16 v[18:33], v[240:243], v[72:75], v[18:33]
	s_waitcnt lgkmcnt(0)
	v_mfma_f32_32x32x16_bf16 v[2:17], v[244:247], v[72:75], v[2:17]
	v_mul_u32_u24_e32 v74, 3, v129
	v_lshlrev_b32_e32 v0, 1, v74
	v_lshl_add_u64 v[66:67], v[124:125], 0, v[0:1]
	s_movk_i32 s25, 0x1000
	v_add_co_u32_e32 v72, vcc, s25, v66
	s_load_dwordx2 s[40:41], s[12:13], 0x20
	s_nop 0
	v_addc_co_u32_e32 v73, vcc, 0, v67, vcc
	s_nop 0
	s_load_dwordx2 s[28:29], s[12:13], 0x100
	v_lshlrev_b32_e32 v76, 2, v116
	v_mov_b32_e32 v77, v1
	v_mov_b32_e32 v123, v1
	s_waitcnt vmcnt(0)
	v_lshlrev_b32_e32 v72, 16, v208
	v_lshlrev_b32_e32 v0, 2, v74
	s_waitcnt lgkmcnt(0)
	v_mov_b32_e32 v73, v211
	v_lshlrev_b64 v[74:75], 13, v[114:115]
	v_lshl_add_u64 v[74:75], s[28:29], 0, v[74:75]
	v_lshl_add_u64 v[74:75], v[74:75], 0, v[76:77]
	v_lshl_add_u64 v[122:123], v[74:75], 0, v[122:123]
	v_lshlrev_b32_e32 v115, 2, v135
	s_waitcnt vmcnt(0)
	v_add_f32_e32 v72, v73, v72
	v_mul_f32_e32 v72, 0xbfb8aa3b, v72
	v_exp_f32_e32 v72, v72
	s_nop 0
	v_add_f32_e32 v72, 1.0, v72
	v_rcp_f32_e32 v72, v72
	s_nop 0
	v_pk_mul_f32 v[2:3], v[2:3], v[72:73] op_sel_hi:[1,0]
	v_pk_mul_f32 v[4:5], v[4:5], v[72:73] op_sel_hi:[1,0]
	global_store_dwordx4 v[122:123], v[2:5], off offset:384
	v_pk_mul_f32 v[18:19], v[18:19], v[72:73] op_sel_hi:[1,0]
	v_pk_mul_f32 v[20:21], v[20:21], v[72:73] op_sel_hi:[1,0]
	v_pk_mul_f32 v[2:3], v[6:7], v[72:73] op_sel_hi:[1,0]
	v_pk_mul_f32 v[4:5], v[8:9], v[72:73] op_sel_hi:[1,0]
	global_store_dwordx4 v[122:123], v[2:5], off offset:416
	global_store_dwordx4 v[122:123], v[18:21], off offset:256
	v_pk_mul_f32 v[50:51], v[50:51], v[72:73] op_sel_hi:[1,0]
	v_pk_mul_f32 v[2:3], v[10:11], v[72:73] op_sel_hi:[1,0]
	v_pk_mul_f32 v[4:5], v[12:13], v[72:73] op_sel_hi:[1,0]
	global_store_dwordx4 v[122:123], v[2:5], off offset:448
	v_pk_mul_f32 v[18:19], v[22:23], v[72:73] op_sel_hi:[1,0]
	v_pk_mul_f32 v[20:21], v[24:25], v[72:73] op_sel_hi:[1,0]
	v_pk_mul_f32 v[2:3], v[14:15], v[72:73] op_sel_hi:[1,0]
	v_pk_mul_f32 v[4:5], v[16:17], v[72:73] op_sel_hi:[1,0]
	global_store_dwordx4 v[122:123], v[2:5], off offset:480
	global_store_dwordx4 v[122:123], v[18:21], off offset:288
	v_pk_mul_f32 v[52:53], v[52:53], v[72:73] op_sel_hi:[1,0]
	v_xor_b32_e32 v2, 1, v160
	v_cmp_lt_i32_e32 vcc, v2, v128
	v_pk_mul_f32 v[18:19], v[26:27], v[72:73] op_sel_hi:[1,0]
	v_pk_mul_f32 v[20:21], v[28:29], v[72:73] op_sel_hi:[1,0]
	v_cndmask_b32_e32 v2, v160, v2, vcc
	v_lshlrev_b32_e32 v6, 2, v2
	v_xor_b32_e32 v2, 2, v160
	v_cmp_lt_i32_e32 vcc, v2, v128
	global_store_dwordx4 v[122:123], v[18:21], off offset:320
	ds_bpermute_b32 v4, v6, v137
	v_cndmask_b32_e32 v2, v160, v2, vcc
	v_pk_mul_f32 v[18:19], v[30:31], v[72:73] op_sel_hi:[1,0]
	v_pk_mul_f32 v[20:21], v[32:33], v[72:73] op_sel_hi:[1,0]
	global_store_dwordx4 v[122:123], v[18:21], off offset:352
	v_lshlrev_b32_e32 v8, 2, v2
	ds_bpermute_b32 v2, v6, v138
	ds_bpermute_b32 v7, v6, v136
	ds_bpermute_b32 v10, v6, v133
	ds_bpermute_b32 v12, v6, v147
	ds_bpermute_b32 v14, v6, v148
	ds_bpermute_b32 v16, v6, v146
	ds_bpermute_b32 v18, v6, v140
	ds_bpermute_b32 v20, v6, v152
	ds_bpermute_b32 v22, v6, v151
	ds_bpermute_b32 v24, v6, v150
	ds_bpermute_b32 v26, v6, v149
	ds_bpermute_b32 v28, v6, v71
	ds_bpermute_b32 v30, v6, v70
	ds_bpermute_b32 v32, v6, v69
	ds_bpermute_b32 v6, v6, v68
	s_waitcnt lgkmcnt(14)
	v_add_f32_e32 v2, v138, v2
	v_add_f32_e32 v4, v137, v4
	s_waitcnt lgkmcnt(13)
	v_add_f32_e32 v7, v136, v7
	s_waitcnt lgkmcnt(12)
	v_add_f32_e32 v10, v133, v10
	s_waitcnt lgkmcnt(11)
	v_add_f32_e32 v12, v147, v12
	s_waitcnt lgkmcnt(10)
	v_add_f32_e32 v14, v148, v14
	s_waitcnt lgkmcnt(9)
	v_add_f32_e32 v16, v146, v16
	s_waitcnt lgkmcnt(8)
	v_add_f32_e32 v18, v140, v18
	s_waitcnt lgkmcnt(7)
	v_add_f32_e32 v20, v152, v20
	s_waitcnt lgkmcnt(6)
	v_add_f32_e32 v22, v151, v22
	s_waitcnt lgkmcnt(5)
	v_add_f32_e32 v24, v150, v24
	s_waitcnt lgkmcnt(4)
	v_add_f32_e32 v26, v149, v26
	s_waitcnt lgkmcnt(3)
	v_add_f32_e32 v28, v71, v28
	s_waitcnt lgkmcnt(2)
	v_add_f32_e32 v30, v70, v30
	s_waitcnt lgkmcnt(1)
	v_add_f32_e32 v32, v69, v32
	s_waitcnt lgkmcnt(0)
	v_add_f32_e32 v6, v68, v6
	ds_bpermute_b32 v3, v8, v2
	ds_bpermute_b32 v5, v8, v4
	ds_bpermute_b32 v9, v8, v7
	ds_bpermute_b32 v11, v8, v10
	ds_bpermute_b32 v13, v8, v12
	ds_bpermute_b32 v15, v8, v14
	ds_bpermute_b32 v17, v8, v16
	ds_bpermute_b32 v19, v8, v18
	ds_bpermute_b32 v21, v8, v20
	ds_bpermute_b32 v23, v8, v22
	ds_bpermute_b32 v25, v8, v24
	ds_bpermute_b32 v27, v8, v26
	ds_bpermute_b32 v29, v8, v28
	ds_bpermute_b32 v31, v8, v30
	ds_bpermute_b32 v33, v8, v32
	ds_bpermute_b32 v8, v8, v6
	v_pk_mul_f32 v[34:35], v[34:35], v[72:73] op_sel_hi:[1,0]
	v_pk_mul_f32 v[36:37], v[36:37], v[72:73] op_sel_hi:[1,0]
	global_store_dwordx4 v[122:123], v[50:53], off
	global_store_dwordx4 v[122:123], v[34:37], off offset:128
	v_cmp_eq_u32_e32 vcc, 0, v127
	v_pk_mul_f32 v[50:51], v[54:55], v[72:73] op_sel_hi:[1,0]
	v_pk_mul_f32 v[52:53], v[56:57], v[72:73] op_sel_hi:[1,0]
	v_pk_mul_f32 v[34:35], v[38:39], v[72:73] op_sel_hi:[1,0]
	v_pk_mul_f32 v[36:37], v[40:41], v[72:73] op_sel_hi:[1,0]
	global_store_dwordx4 v[122:123], v[50:53], off offset:32
	global_store_dwordx4 v[122:123], v[34:37], off offset:160
	s_nop 0
	v_pk_mul_f32 v[50:51], v[58:59], v[72:73] op_sel_hi:[1,0]
	v_pk_mul_f32 v[52:53], v[60:61], v[72:73] op_sel_hi:[1,0]
	v_pk_mul_f32 v[34:35], v[42:43], v[72:73] op_sel_hi:[1,0]
	v_pk_mul_f32 v[36:37], v[44:45], v[72:73] op_sel_hi:[1,0]
	global_store_dwordx4 v[122:123], v[50:53], off offset:64
	global_store_dwordx4 v[122:123], v[34:37], off offset:192
	s_nop 0
	v_pk_mul_f32 v[50:51], v[62:63], v[72:73] op_sel_hi:[1,0]
	v_pk_mul_f32 v[52:53], v[64:65], v[72:73] op_sel_hi:[1,0]
	v_pk_mul_f32 v[34:35], v[46:47], v[72:73] op_sel_hi:[1,0]
	v_pk_mul_f32 v[36:37], v[48:49], v[72:73] op_sel_hi:[1,0]
	global_store_dwordx4 v[122:123], v[50:53], off offset:96
	global_store_dwordx4 v[122:123], v[34:37], off offset:224
	s_waitcnt lgkmcnt(0)
	s_barrier
	s_and_saveexec_b64 s[42:43], vcc
	s_cbranch_execz .LBB0_312
	v_add_f32_e32 v2, v2, v3
	v_or_b32_e32 v3, v126, v121
	v_lshlrev_b32_e32 v3, 7, v3
	v_add_f32_e32 v4, v4, v5
	v_add3_u32 v3, 16, v3, v115
	v_add_f32_e32 v6, v6, v8
	v_add_f32_e32 v8, v32, v33
	v_add_f32_e32 v30, v30, v31
	v_add_f32_e32 v28, v28, v29
	v_add_f32_e32 v26, v26, v27
	v_add_f32_e32 v24, v24, v25
	v_add_f32_e32 v22, v22, v23
	v_add_f32_e32 v20, v20, v21
	v_add_f32_e32 v18, v18, v19
	v_add_f32_e32 v16, v16, v17
	v_add_f32_e32 v14, v14, v15
	v_add_f32_e32 v12, v12, v13
	v_add_f32_e32 v10, v10, v11
	v_add_f32_e32 v7, v7, v9
	ds_write2_b32 v3, v2, v4 offset1:2
	ds_write2_b32 v3, v7, v10 offset0:4 offset1:6
	ds_write2_b32 v3, v12, v14 offset0:8 offset1:10
	ds_write2_b32 v3, v16, v18 offset0:12 offset1:14
	ds_write2_b32 v3, v20, v22 offset0:16 offset1:18
	ds_write2_b32 v3, v24, v26 offset0:20 offset1:22
	ds_write2_b32 v3, v28, v30 offset0:24 offset1:26
	ds_write2_b32 v3, v8, v6 offset0:28 offset1:30
